# group-barrier polling loops spin without s_sleep
# speedup vs baseline: 1.0417x; 1.0091x over previous
.LBB0_308:
	v_mov_b32_e32 v0, s33
	ds_read_b32 v0, v0 offset:8
	s_waitcnt lgkmcnt(0)
	v_cmp_gt_u32_e32 vcc, s0, v0
	s_cbranch_vccnz .LBB0_308

.LBB0_893:
	v_mov_b32_e32 v0, s33
	ds_read_b32 v0, v0 offset:8
	s_waitcnt lgkmcnt(0)
	v_cmp_gt_u32_e32 vcc, s0, v0
	s_cbranch_vccnz .LBB0_893
	s_branch .LBB0_290

.LBB0_1048:
	v_mov_b32_e32 v6, s33
	ds_read_b32 v6, v6 offset:8
	s_waitcnt lgkmcnt(0)
	v_cmp_gt_u32_e32 vcc, s8, v6
	s_cbranch_vccnz .LBB0_1048

.LBB0_1053:
	v_mov_b32_e32 v0, s33
	ds_read_b32 v0, v0 offset:8
	s_waitcnt lgkmcnt(0)
	v_cmp_gt_u32_e32 vcc, s20, v0
	s_cbranch_vccnz .LBB0_1053

.LBB0_1355:
	v_mov_b32_e32 v4, s33
	ds_read_b32 v4, v4 offset:8
	s_waitcnt lgkmcnt(0)
	v_cmp_gt_u32_e32 vcc, s14, v4
	s_cbranch_vccnz .LBB0_1355

.LBB0_1360:
	v_mov_b32_e32 v0, s33
	ds_read_b32 v0, v0 offset:8
	s_waitcnt lgkmcnt(0)
	v_cmp_gt_u32_e32 vcc, s14, v0
	s_cbranch_vccnz .LBB0_1360

.LBB0_1365:
	v_mov_b32_e32 v5, s33
	ds_read_b32 v5, v5 offset:8
	s_waitcnt lgkmcnt(0)
	v_cmp_gt_u32_e32 vcc, s31, v5
	s_cbranch_vccnz .LBB0_1365

.LBB0_1377:
	v_mov_b32_e32 v0, s33
	ds_read_b32 v0, v0 offset:8
	s_waitcnt lgkmcnt(0)
	v_cmp_gt_u32_e32 vcc, s17, v0
	s_cbranch_vccnz .LBB0_1377

.LBB0_1390:
	v_mov_b32_e32 v0, s33
	ds_read_b32 v0, v0 offset:8
	s_waitcnt lgkmcnt(0)
	v_cmp_gt_u32_e32 vcc, s4, v0
	s_cbranch_vccnz .LBB0_1390

.LBB0_1397:
	v_mov_b32_e32 v4, s33
	ds_read_b32 v4, v4 offset:8
	s_waitcnt lgkmcnt(0)
	v_cmp_gt_u32_e32 vcc, s4, v4
	s_cbranch_vccnz .LBB0_1397

.LBB0_1407:
	v_mov_b32_e32 v5, s33
	ds_read_b32 v5, v5 offset:8
	s_waitcnt lgkmcnt(0)
	v_cmp_gt_u32_e32 vcc, s81, v5
	s_cbranch_vccnz .LBB0_1407

.LBB0_1432:
	v_mov_b32_e32 v0, s33
	ds_read_b32 v0, v0 offset:8
	s_waitcnt lgkmcnt(0)
	v_cmp_gt_u32_e32 vcc, s81, v0
	s_cbranch_vccnz .LBB0_1432
